# v98 plus nt (streaming) hint on the out-GEMM A-tile LDS-DMA loads (keep the shared weight slices in L2)
# baseline (speedup 1.0000x reference)
; #define PG8_STAGE(bufoff, gbase, voff) do { _Pragma("unroll") for (int _i = 0; _i < 2; ++_i) \
;         __builtin_amdgcn_global_load_lds((const unsigned*)((const char*)(gbase) + (voff)[_i]), (LAS unsigned*)(lds + (bufoff) + ldsw + _i * 8192), 16, 0, 0); } while (0)
; #define PG8_LDA(dst, b, h) do { _Pragma("unroll") for (int m = 0; m < 4; ++m) _Pragma("unroll") for (int k = 0; k < 2; ++k) dst[m][k] = *(const LAS bf16x8*)(lds + PG8_SA(b, h) + aoff + m * 2048 + k * 1024); } while (0)
; #define PG8_LDB(dst, b, h) do { _Pragma("unroll") for (int n = 0; n < 2; ++n) _Pragma("unroll") for (int k = 0; k < 2; ++k) dst[n][k] = *(const LAS bf16x8*)(lds + PG8_SB(b, h) + boff + n * 2048 + k * 1024); } while (0)
; #define PG8_MMA(ai, bj, At, Bt) do { __builtin_amdgcn_s_setprio(1); _Pragma("unroll") for (int m = 0; m < 4; ++m) _Pragma("unroll") for (int n = 0; n < 2; ++n) _Pragma("unroll") for (int k = 0; k < 2; ++k) \
;         acc[ai][bj][m][n] = __builtin_amdgcn_mfma_f32_16x16x32_bf16(Bt[n][k], At[m][k], acc[ai][bj][m][n], 0, 0, 0); __builtin_amdgcn_s_setprio(0); } while (0)
; #define PG8_WAIT_L(n) asm volatile("s_waitcnt lgkmcnt(" #n ")" ::: "memory")
; #define PG8_BAR __builtin_amdgcn_s_barrier()
; #define PG8_SCHED __builtin_amdgcn_sched_barrier(0)
; template <class Epi>
; DI void gemm_phase(LAS unsigned char* lds, const Gemm g, const StaticOrder& S_, const Epi& E) {
;     ...
;             const bool last = (t == nt - 2);
;             const bool hA = (t >= ksplit), hB = (t + 2 >= ksplit);
;             const char* a1 = (hA ? cA1 : cA0) + (size_t)(t + 1) * kstep;
;             const char* a2 = last ? nA0 : (hB ? cA1 : cA0) + (size_t)(t + 2) * kstep; const char* b2 = last ? nB0 : (hB ? cB1 : cB0) + (size_t)(t + 2) * kstep;
;             const char* a3 = a2 + kstep; const char* b3 = b2 + kstep;
;             PG8_LDB(B0, 0, 0); PG8_SCHED; PG8_LDA(At, 0, 0); PG8_STAGE(PG8_SA(1, 1), a1 + hstepA, voffA);
;             PG8_WAIT_L(8); PG8_BAR; PG8_WAIT_L(0); PG8_MMA(0, 0, At, B0); PG8_BAR; PG8_SCHED;
;             PG8_LDB(B1, 0, 1); PG8_STAGE(PG8_SB(0, 0), b2, voffB);
;             PG8_BAR; PG8_WAIT_L(0); PG8_MMA(0, 1, At, B1); PG8_BAR;
;             PG8_LDA(At, 0, 1); PG8_STAGE(PG8_SA(0, 0), a2, voffA);
;             PG8_BAR; PG8_WAIT_L(0); PG8_MMA(1, 0, At, B0); PG8_BAR; PG8_SCHED;
.LBB0_525:
	s_add_i32 s72, s46, 2
	s_cmp_gt_u32 s72, 29
	s_cselect_b64 s[48:49], -1, 0
	s_and_b64 vcc, s[48:49], exec
	s_cselect_b32 s48, s37, s40
	s_cselect_b32 s47, s39, s41
	s_cselect_b32 s49, s69, s43
	s_cselect_b32 s73, s68, s42
	s_add_u32 s48, s48, s44
	s_addc_u32 s47, s47, s45
	s_add_u32 s48, s48, 0xfff80080
	s_addc_u32 s47, s47, -1
	ds_read_b128 v[158:161], v153
	ds_read_b128 v[162:165], v153 offset:1024
	ds_read_b128 v[166:169], v153 offset:2048
	ds_read_b128 v[170:173], v153 offset:3072
	s_add_u32 s73, s73, s44
	s_addc_u32 s49, s49, s45
	s_add_u32 s73, s73, 0xfff80080
	s_addc_u32 s74, s49, -1
	s_cmp_eq_u32 s46, 28
	s_cselect_b32 s46, s71, s73
	s_cselect_b32 s49, s23, s47
	s_cselect_b32 s48, s70, s48
	s_cselect_b32 s47, s21, s74
	v_lshl_add_u64 v[208:209], v[146:147], 0, s[44:45]
	s_add_i32 m0, s54, 0xc000
	ds_read_b128 v[174:177], v154
	ds_read_b128 v[178:181], v154 offset:1024
	ds_read_b128 v[182:185], v154 offset:2048
	ds_read_b128 v[186:189], v154 offset:3072
	ds_read_b128 v[190:193], v154 offset:4096
	ds_read_b128 v[194:197], v154 offset:5120
	ds_read_b128 v[198:201], v154 offset:6144
	ds_read_b128 v[204:207], v154 offset:7168
	global_load_lds_dwordx4 v[208:209], off nt
	v_lshl_add_u64 v[208:209], v[148:149], 0, s[44:45]
	s_add_i32 m0, s54, 0xe000
	s_nop 0
	global_load_lds_dwordx4 v[208:209], off nt
	s_waitcnt lgkmcnt(8)
	s_setprio 1
	s_barrier
	s_waitcnt lgkmcnt(0)
	v_mfma_f32_16x16x32_bf16 v[124:127], v[158:161], v[174:177], v[124:127]
	v_mfma_f32_16x16x32_bf16 v[120:123], v[166:169], v[174:177], v[120:123]
	v_mfma_f32_16x16x32_bf16 v[108:111], v[158:161], v[182:185], v[108:111]
	v_mfma_f32_16x16x32_bf16 v[104:107], v[166:169], v[182:185], v[104:107]
	v_mfma_f32_16x16x32_bf16 v[92:95], v[158:161], v[190:193], v[92:95]
	v_mfma_f32_16x16x32_bf16 v[88:91], v[166:169], v[190:193], v[88:91]
	v_mfma_f32_16x16x32_bf16 v[76:79], v[158:161], v[198:201], v[76:79]
	v_mfma_f32_16x16x32_bf16 v[72:75], v[166:169], v[198:201], v[72:75]
	v_mfma_f32_16x16x32_bf16 v[124:127], v[162:165], v[178:181], v[124:127]
	v_mfma_f32_16x16x32_bf16 v[120:123], v[170:173], v[178:181], v[120:123]
	v_mfma_f32_16x16x32_bf16 v[108:111], v[162:165], v[186:189], v[108:111]
	v_mfma_f32_16x16x32_bf16 v[104:107], v[170:173], v[186:189], v[104:107]
	v_mfma_f32_16x16x32_bf16 v[92:95], v[162:165], v[194:197], v[92:95]
	v_mfma_f32_16x16x32_bf16 v[88:91], v[170:173], v[194:197], v[88:91]
	v_mfma_f32_16x16x32_bf16 v[76:79], v[162:165], v[204:207], v[76:79]
	v_mfma_f32_16x16x32_bf16 v[72:75], v[170:173], v[204:207], v[72:75]
	s_setprio 0
	s_barrier
	s_add_i32 s73, s66, s53
	v_lshl_add_u64 v[224:225], s[46:47], 0, v[130:131]
	s_mov_b32 m0, s73
	ds_read_b128 v[208:211], v155
	ds_read_b128 v[212:215], v155 offset:1024
	ds_read_b128 v[216:219], v155 offset:2048
	ds_read_b128 v[220:223], v155 offset:3072
	global_load_lds_dwordx4 v[224:225], off
	v_lshl_add_u64 v[226:227], s[46:47], 0, v[134:135]
	s_add_i32 m0, s73, 0x2000
	s_nop 0
	global_load_lds_dwordx4 v[226:227], off
	s_setprio 1
	s_barrier
	s_waitcnt lgkmcnt(0)
	v_mfma_f32_16x16x32_bf16 v[116:119], v[208:211], v[174:177], v[116:119]
	v_mfma_f32_16x16x32_bf16 v[112:115], v[216:219], v[174:177], v[112:115]
	v_mfma_f32_16x16x32_bf16 v[100:103], v[208:211], v[182:185], v[100:103]
	v_mfma_f32_16x16x32_bf16 v[96:99], v[216:219], v[182:185], v[96:99]
	v_mfma_f32_16x16x32_bf16 v[84:87], v[208:211], v[190:193], v[84:87]
	v_mfma_f32_16x16x32_bf16 v[80:83], v[216:219], v[190:193], v[80:83]
	v_mfma_f32_16x16x32_bf16 v[68:71], v[208:211], v[198:201], v[68:71]
	v_mfma_f32_16x16x32_bf16 v[64:67], v[216:219], v[198:201], v[64:67]
	v_mfma_f32_16x16x32_bf16 v[116:119], v[212:215], v[178:181], v[116:119]
	v_mfma_f32_16x16x32_bf16 v[112:115], v[220:223], v[178:181], v[112:115]
	v_mfma_f32_16x16x32_bf16 v[100:103], v[212:215], v[186:189], v[100:103]
	v_mfma_f32_16x16x32_bf16 v[96:99], v[220:223], v[186:189], v[96:99]
	v_mfma_f32_16x16x32_bf16 v[84:87], v[212:215], v[194:197], v[84:87]
	v_mfma_f32_16x16x32_bf16 v[80:83], v[220:223], v[194:197], v[80:83]
	v_mfma_f32_16x16x32_bf16 v[68:71], v[212:215], v[204:207], v[68:71]
	v_mfma_f32_16x16x32_bf16 v[64:67], v[220:223], v[204:207], v[64:67]
	s_setprio 0
	s_mov_b32 m0, s54
	v_lshl_add_u64 v[228:229], s[48:49], 0, v[128:129]
	s_barrier
	ds_read_b128 v[174:177], v154 offset:16384
	ds_read_b128 v[178:181], v154 offset:17408
	ds_read_b128 v[182:185], v154 offset:18432
	ds_read_b128 v[186:189], v154 offset:19456
	ds_read_b128 v[190:193], v154 offset:20480
	ds_read_b128 v[194:197], v154 offset:21504
	ds_read_b128 v[198:201], v154 offset:22528
	ds_read_b128 v[204:207], v154 offset:23552
	global_load_lds_dwordx4 v[228:229], off nt
	v_lshl_add_u64 v[230:231], s[48:49], 0, v[132:133]
	s_mov_b32 m0, s55
	s_nop 0
	global_load_lds_dwordx4 v[230:231], off nt
	s_setprio 1
	s_barrier
	s_waitcnt lgkmcnt(0)
	v_mfma_f32_16x16x32_bf16 v[60:63], v[158:161], v[174:177], v[60:63]
	v_mfma_f32_16x16x32_bf16 v[56:59], v[166:169], v[174:177], v[56:59]
	v_mfma_f32_16x16x32_bf16 v[44:47], v[158:161], v[182:185], v[44:47]
	v_mfma_f32_16x16x32_bf16 v[40:43], v[166:169], v[182:185], v[40:43]
	v_mfma_f32_16x16x32_bf16 v[28:31], v[158:161], v[190:193], v[28:31]
	v_mfma_f32_16x16x32_bf16 v[24:27], v[166:169], v[190:193], v[24:27]
	v_mfma_f32_16x16x32_bf16 v[12:15], v[158:161], v[198:201], v[12:15]
	v_mfma_f32_16x16x32_bf16 v[8:11], v[166:169], v[198:201], v[8:11]
	v_mfma_f32_16x16x32_bf16 v[60:63], v[162:165], v[178:181], v[60:63]
	v_mfma_f32_16x16x32_bf16 v[56:59], v[170:173], v[178:181], v[56:59]
	v_mfma_f32_16x16x32_bf16 v[44:47], v[162:165], v[186:189], v[44:47]
	v_mfma_f32_16x16x32_bf16 v[40:43], v[170:173], v[186:189], v[40:43]
	v_mfma_f32_16x16x32_bf16 v[28:31], v[162:165], v[194:197], v[28:31]
	v_mfma_f32_16x16x32_bf16 v[24:27], v[170:173], v[194:197], v[24:27]
	v_mfma_f32_16x16x32_bf16 v[12:15], v[162:165], v[204:207], v[12:15]
	v_mfma_f32_16x16x32_bf16 v[8:11], v[170:173], v[204:207], v[8:11]
	s_setprio 0
	s_barrier
; #define PG8_STAGE(bufoff, gbase, voff) do { _Pragma("unroll") for (int _i = 0; _i < 2; ++_i) \
;         __builtin_amdgcn_global_load_lds((const unsigned*)((const char*)(gbase) + (voff)[_i]), (LAS unsigned*)(lds + (bufoff) + ldsw + _i * 8192), 16, 0, 0); } while (0)
; #define PG8_LDA(dst, b, h) do { _Pragma("unroll") for (int m = 0; m < 4; ++m) _Pragma("unroll") for (int k = 0; k < 2; ++k) dst[m][k] = *(const LAS bf16x8*)(lds + PG8_SA(b, h) + aoff + m * 2048 + k * 1024); } while (0)
; #define PG8_LDB(dst, b, h) do { _Pragma("unroll") for (int n = 0; n < 2; ++n) _Pragma("unroll") for (int k = 0; k < 2; ++k) dst[n][k] = *(const LAS bf16x8*)(lds + PG8_SB(b, h) + boff + n * 2048 + k * 1024); } while (0)
; #define PG8_MMA(ai, bj, At, Bt) do { __builtin_amdgcn_s_setprio(1); _Pragma("unroll") for (int m = 0; m < 4; ++m) _Pragma("unroll") for (int n = 0; n < 2; ++n) _Pragma("unroll") for (int k = 0; k < 2; ++k) \
;         acc[ai][bj][m][n] = __builtin_amdgcn_mfma_f32_16x16x32_bf16(Bt[n][k], At[m][k], acc[ai][bj][m][n], 0, 0, 0); __builtin_amdgcn_s_setprio(0); } while (0)
; #define PG8_WAIT_V(n) asm volatile("s_waitcnt vmcnt(" #n ")" ::: "memory")
; #define PG8_WAIT_L(n) asm volatile("s_waitcnt lgkmcnt(" #n ")" ::: "memory")
; #define PG8_BAR __builtin_amdgcn_s_barrier()
; #define PG8_SCHED __builtin_amdgcn_sched_barrier(0)
; template <class Epi>
; DI void gemm_phase(LAS unsigned char* lds, const Gemm g, const StaticOrder& S_, const Epi& E) {
;     ...
;             PG8_STAGE(PG8_SB(0, 1), b2 + hstepB, voffB);
;             PG8_WAIT_V(6); PG8_BAR; PG8_MMA(1, 1, At, B1); PG8_BAR;
;             PG8_LDB(B0, 1, 0); PG8_SCHED; PG8_LDA(At, 1, 0); PG8_STAGE(PG8_SA(0, 1), a2 + hstepA, voffA);
;             PG8_WAIT_L(8); PG8_BAR; PG8_WAIT_L(0); PG8_MMA(0, 0, At, B0); PG8_BAR; PG8_SCHED;
;             PG8_LDB(B1, 1, 1); PG8_STAGE(PG8_SB(1, 0), b3, voffB);
;             PG8_BAR; PG8_WAIT_L(0); PG8_MMA(0, 1, At, B1); PG8_BAR;
;             PG8_LDA(At, 1, 1); PG8_STAGE(PG8_SA(1, 0), a3, voffA);
	s_add_u32 s74, s46, 0x80000
	s_addc_u32 s75, s47, 0
	s_add_i32 s73, s67, s53
	v_lshl_add_u64 v[158:159], s[74:75], 0, v[130:131]
	s_mov_b32 m0, s73
	s_nop 0
	global_load_lds_dwordx4 v[158:159], off
	v_lshl_add_u64 v[158:159], s[74:75], 0, v[134:135]
	s_add_i32 m0, s73, 0x2000
	s_nop 0
	global_load_lds_dwordx4 v[158:159], off
	s_waitcnt vmcnt(6)
	s_setprio 1
	s_barrier
	v_mfma_f32_16x16x32_bf16 v[52:55], v[208:211], v[174:177], v[52:55]
	v_mfma_f32_16x16x32_bf16 v[48:51], v[216:219], v[174:177], v[48:51]
	v_mfma_f32_16x16x32_bf16 v[36:39], v[208:211], v[182:185], v[36:39]
	v_mfma_f32_16x16x32_bf16 v[32:35], v[216:219], v[182:185], v[32:35]
	v_mfma_f32_16x16x32_bf16 v[20:23], v[208:211], v[190:193], v[20:23]
	v_mfma_f32_16x16x32_bf16 v[16:19], v[216:219], v[190:193], v[16:19]
	v_mfma_f32_16x16x32_bf16 v[4:7], v[208:211], v[198:201], v[4:7]
	v_mfma_f32_16x16x32_bf16 v[0:3], v[216:219], v[198:201], v[0:3]
	v_mfma_f32_16x16x32_bf16 v[52:55], v[212:215], v[178:181], v[52:55]
	v_mfma_f32_16x16x32_bf16 v[48:51], v[220:223], v[178:181], v[48:51]
	v_mfma_f32_16x16x32_bf16 v[36:39], v[212:215], v[186:189], v[36:39]
	v_mfma_f32_16x16x32_bf16 v[32:35], v[220:223], v[186:189], v[32:35]
	v_mfma_f32_16x16x32_bf16 v[20:23], v[212:215], v[194:197], v[20:23]
	v_mfma_f32_16x16x32_bf16 v[16:19], v[220:223], v[194:197], v[16:19]
	v_mfma_f32_16x16x32_bf16 v[4:7], v[212:215], v[204:207], v[4:7]
	v_mfma_f32_16x16x32_bf16 v[0:3], v[220:223], v[204:207], v[0:3]
	s_setprio 0
	s_add_i32 s73, 0, 0x18000
	v_add_u32_e32 v136, s73, v151
	s_barrier
	ds_read_b128 v[158:161], v136
	ds_read_b128 v[162:165], v136 offset:1024
	ds_read_b128 v[166:169], v136 offset:2048
	ds_read_b128 v[170:173], v136 offset:3072
	s_add_u32 s48, s48, 0x80000
	s_addc_u32 s49, s49, 0
	s_mov_b32 m0, s56
	v_lshl_add_u64 v[208:209], s[48:49], 0, v[128:129]
	ds_read_b128 v[174:177], v154 offset:32768
	ds_read_b128 v[178:181], v154 offset:33792
	ds_read_b128 v[182:185], v154 offset:34816
	ds_read_b128 v[186:189], v154 offset:35840
	ds_read_b128 v[190:193], v154 offset:36864
	ds_read_b128 v[194:197], v154 offset:37888
	ds_read_b128 v[198:201], v154 offset:38912
	ds_read_b128 v[204:207], v154 offset:39936
	global_load_lds_dwordx4 v[208:209], off nt
	v_lshl_add_u64 v[208:209], s[48:49], 0, v[132:133]
	s_mov_b32 m0, s57
	s_nop 0
	global_load_lds_dwordx4 v[208:209], off nt
	s_waitcnt lgkmcnt(8)
	s_setprio 1
	s_barrier
	s_waitcnt lgkmcnt(0)
	v_mfma_f32_16x16x32_bf16 v[124:127], v[158:161], v[174:177], v[124:127]
	v_mfma_f32_16x16x32_bf16 v[120:123], v[166:169], v[174:177], v[120:123]
	v_mfma_f32_16x16x32_bf16 v[108:111], v[158:161], v[182:185], v[108:111]
	v_mfma_f32_16x16x32_bf16 v[104:107], v[166:169], v[182:185], v[104:107]
	v_mfma_f32_16x16x32_bf16 v[92:95], v[158:161], v[190:193], v[92:95]
	v_mfma_f32_16x16x32_bf16 v[88:91], v[166:169], v[190:193], v[88:91]
	v_mfma_f32_16x16x32_bf16 v[76:79], v[158:161], v[198:201], v[76:79]
	v_mfma_f32_16x16x32_bf16 v[72:75], v[166:169], v[198:201], v[72:75]
	v_mfma_f32_16x16x32_bf16 v[124:127], v[162:165], v[178:181], v[124:127]
	v_mfma_f32_16x16x32_bf16 v[120:123], v[170:173], v[178:181], v[120:123]
	v_mfma_f32_16x16x32_bf16 v[108:111], v[162:165], v[186:189], v[108:111]
	v_mfma_f32_16x16x32_bf16 v[104:107], v[170:173], v[186:189], v[104:107]
	v_mfma_f32_16x16x32_bf16 v[92:95], v[162:165], v[194:197], v[92:95]
	v_mfma_f32_16x16x32_bf16 v[88:91], v[170:173], v[194:197], v[88:91]
	v_mfma_f32_16x16x32_bf16 v[76:79], v[162:165], v[204:207], v[76:79]
	v_mfma_f32_16x16x32_bf16 v[72:75], v[170:173], v[204:207], v[72:75]
	s_setprio 0
	s_barrier
	s_add_i32 s48, 0, 0x1c000
	s_add_i32 s49, s73, s53
	v_add_u32_e32 v136, s48, v151
	v_lshl_add_u64 v[224:225], v[224:225], 0, s[16:17]
	s_mov_b32 m0, s49
	ds_read_b128 v[208:211], v136
	ds_read_b128 v[212:215], v136 offset:1024
	ds_read_b128 v[216:219], v136 offset:2048
	ds_read_b128 v[220:223], v136 offset:3072
	global_load_lds_dwordx4 v[224:225], off
	v_lshl_add_u64 v[224:225], v[226:227], 0, s[16:17]
	s_add_i32 m0, s49, 0x2000
	s_nop 0
	global_load_lds_dwordx4 v[224:225], off
	s_setprio 1
	s_barrier
	s_waitcnt lgkmcnt(0)
	v_mfma_f32_16x16x32_bf16 v[116:119], v[208:211], v[174:177], v[116:119]
	v_mfma_f32_16x16x32_bf16 v[112:115], v[216:219], v[174:177], v[112:115]
	v_mfma_f32_16x16x32_bf16 v[100:103], v[208:211], v[182:185], v[100:103]
	v_mfma_f32_16x16x32_bf16 v[96:99], v[216:219], v[182:185], v[96:99]
	v_mfma_f32_16x16x32_bf16 v[84:87], v[208:211], v[190:193], v[84:87]
	v_mfma_f32_16x16x32_bf16 v[80:83], v[216:219], v[190:193], v[80:83]
	v_mfma_f32_16x16x32_bf16 v[68:71], v[208:211], v[198:201], v[68:71]
	v_mfma_f32_16x16x32_bf16 v[64:67], v[216:219], v[198:201], v[64:67]
	v_mfma_f32_16x16x32_bf16 v[116:119], v[212:215], v[178:181], v[116:119]
	v_mfma_f32_16x16x32_bf16 v[112:115], v[220:223], v[178:181], v[112:115]
	v_mfma_f32_16x16x32_bf16 v[100:103], v[212:215], v[186:189], v[100:103]
	v_mfma_f32_16x16x32_bf16 v[96:99], v[220:223], v[186:189], v[96:99]
	v_mfma_f32_16x16x32_bf16 v[84:87], v[212:215], v[194:197], v[84:87]
	v_mfma_f32_16x16x32_bf16 v[80:83], v[220:223], v[194:197], v[80:83]
	v_mfma_f32_16x16x32_bf16 v[68:71], v[212:215], v[204:207], v[68:71]
	v_mfma_f32_16x16x32_bf16 v[64:67], v[220:223], v[204:207], v[64:67]
	s_setprio 0
	s_mov_b32 m0, s59
	v_lshl_add_u64 v[224:225], v[228:229], 0, s[16:17]
	s_barrier
	ds_read_b128 v[174:177], v154 offset:49152
	ds_read_b128 v[178:181], v154 offset:50176
	ds_read_b128 v[182:185], v154 offset:51200
	ds_read_b128 v[186:189], v154 offset:52224
	ds_read_b128 v[190:193], v154 offset:53248
	ds_read_b128 v[194:197], v154 offset:54272
	ds_read_b128 v[198:201], v154 offset:55296
	ds_read_b128 v[204:207], v154 offset:56320
	global_load_lds_dwordx4 v[224:225], off nt
	v_lshl_add_u64 v[224:225], v[230:231], 0, s[16:17]
	s_mov_b32 m0, s60
	s_nop 0
	global_load_lds_dwordx4 v[224:225], off nt
	s_setprio 1
	s_barrier
; #define PG8_STAGE(bufoff, gbase, voff) do { _Pragma("unroll") for (int _i = 0; _i < 2; ++_i) \
;         __builtin_amdgcn_global_load_lds((const unsigned*)((const char*)(gbase) + (voff)[_i]), (LAS unsigned*)(lds + (bufoff) + ldsw + _i * 8192), 16, 0, 0); } while (0)
; #define PG8_MMA(ai, bj, At, Bt) do { __builtin_amdgcn_s_setprio(1); _Pragma("unroll") for (int m = 0; m < 4; ++m) _Pragma("unroll") for (int n = 0; n < 2; ++n) _Pragma("unroll") for (int k = 0; k < 2; ++k) \
;         acc[ai][bj][m][n] = __builtin_amdgcn_mfma_f32_16x16x32_bf16(Bt[n][k], At[m][k], acc[ai][bj][m][n], 0, 0, 0); __builtin_amdgcn_s_setprio(0); } while (0)
; #define PG8_WAIT_V(n) asm volatile("s_waitcnt vmcnt(" #n ")" ::: "memory")
; #define PG8_BAR __builtin_amdgcn_s_barrier()
; template <class Epi>
; DI void gemm_phase(LAS unsigned char* lds, const Gemm g, const StaticOrder& S_, const Epi& E) {
;     ...
;             PG8_STAGE(PG8_SB(1, 1), b3 + hstepB, voffB);
;             PG8_WAIT_V(6); PG8_BAR; PG8_MMA(1, 1, At, B1); PG8_BAR;
;     DI void operator()(const f32x4 (&acc)[2][2][4][2], const pg8::Unit& u, int wr, int wc, int fr, int fq) const {
;         unsigned char* o2 = ws + WS_OUT2; float* ssq = (float*)(ws + WS_SSQ);
;         const unsigned r0_ = (unsigned)(u.pm * 256 + wr * 64 + fr), c0_ = (unsigned)(u.pn * 256 + wc * 32 + 8 * fq) * 2u;
; #pragma unroll
;         for (int ai = 0; ai < 2; ++ai)
; #pragma unroll
;             for (int m = 0; m < 4; ++m) {
;                 const unsigned row = r0_ + ai * 128 + m * 16; float s = 0.f;
; #pragma unroll
;                 for (int bj = 0; bj < 2; ++bj) {
;                     const f32x4 v0 = acc[ai][bj][m][0], v1 = acc[ai][bj][m][1];
;                     s += v0[0] * v0[0] + v0[1] * v0[1] + v0[2] * v0[2] + v0[3] * v0[3] + v1[0] * v1[0] + v1[1] * v1[1] + v1[2] * v1[2] + v1[3] * v1[3];
	s_waitcnt lgkmcnt(0)
	v_mfma_f32_16x16x32_bf16 v[60:63], v[158:161], v[174:177], v[60:63]
	v_mfma_f32_16x16x32_bf16 v[56:59], v[166:169], v[174:177], v[56:59]
	v_mfma_f32_16x16x32_bf16 v[44:47], v[158:161], v[182:185], v[44:47]
	v_mfma_f32_16x16x32_bf16 v[40:43], v[166:169], v[182:185], v[40:43]
	v_mfma_f32_16x16x32_bf16 v[28:31], v[158:161], v[190:193], v[28:31]
	v_mfma_f32_16x16x32_bf16 v[24:27], v[166:169], v[190:193], v[24:27]
	v_mfma_f32_16x16x32_bf16 v[12:15], v[158:161], v[198:201], v[12:15]
	v_mfma_f32_16x16x32_bf16 v[8:11], v[166:169], v[198:201], v[8:11]
	v_mfma_f32_16x16x32_bf16 v[60:63], v[162:165], v[178:181], v[60:63]
	v_mfma_f32_16x16x32_bf16 v[56:59], v[170:173], v[178:181], v[56:59]
	v_mfma_f32_16x16x32_bf16 v[44:47], v[162:165], v[186:189], v[44:47]
	v_mfma_f32_16x16x32_bf16 v[40:43], v[170:173], v[186:189], v[40:43]
	v_mfma_f32_16x16x32_bf16 v[28:31], v[162:165], v[194:197], v[28:31]
	v_mfma_f32_16x16x32_bf16 v[24:27], v[170:173], v[194:197], v[24:27]
	v_mfma_f32_16x16x32_bf16 v[12:15], v[162:165], v[204:207], v[12:15]
	v_mfma_f32_16x16x32_bf16 v[8:11], v[170:173], v[204:207], v[8:11]
	s_setprio 0
	s_barrier
	s_add_u32 s46, s46, 0x80080
	s_addc_u32 s47, s47, 0
	s_add_i32 s48, s48, s53
	v_lshl_add_u64 v[158:159], s[46:47], 0, v[130:131]
	s_mov_b32 m0, s48
	s_nop 0
	global_load_lds_dwordx4 v[158:159], off
	v_lshl_add_u64 v[158:159], s[46:47], 0, v[134:135]
	s_add_i32 m0, s48, 0x2000
	s_nop 0
	global_load_lds_dwordx4 v[158:159], off
	s_waitcnt vmcnt(6)
	s_setprio 1
	s_barrier
	v_mfma_f32_16x16x32_bf16 v[52:55], v[208:211], v[174:177], v[52:55]
	v_mfma_f32_16x16x32_bf16 v[48:51], v[216:219], v[174:177], v[48:51]
	v_mfma_f32_16x16x32_bf16 v[36:39], v[208:211], v[182:185], v[36:39]
	v_mfma_f32_16x16x32_bf16 v[32:35], v[216:219], v[182:185], v[32:35]
	v_mfma_f32_16x16x32_bf16 v[20:23], v[208:211], v[190:193], v[20:23]
	v_mfma_f32_16x16x32_bf16 v[16:19], v[216:219], v[190:193], v[16:19]
	v_mfma_f32_16x16x32_bf16 v[4:7], v[208:211], v[198:201], v[4:7]
	v_mfma_f32_16x16x32_bf16 v[0:3], v[216:219], v[198:201], v[0:3]
	v_mfma_f32_16x16x32_bf16 v[52:55], v[212:215], v[178:181], v[52:55]
	v_mfma_f32_16x16x32_bf16 v[48:51], v[220:223], v[178:181], v[48:51]
	v_mfma_f32_16x16x32_bf16 v[36:39], v[212:215], v[186:189], v[36:39]
	v_mfma_f32_16x16x32_bf16 v[32:35], v[220:223], v[186:189], v[32:35]
	v_mfma_f32_16x16x32_bf16 v[20:23], v[212:215], v[194:197], v[20:23]
	v_mfma_f32_16x16x32_bf16 v[16:19], v[220:223], v[194:197], v[16:19]
	v_mfma_f32_16x16x32_bf16 v[4:7], v[212:215], v[204:207], v[4:7]
	v_mfma_f32_16x16x32_bf16 v[0:3], v[220:223], v[204:207], v[0:3]
	s_setprio 0
	s_add_u32 s44, s44, 0x100
	s_addc_u32 s45, s45, 0
	s_mov_b32 s46, s72
	s_barrier
	s_cbranch_vccz .LBB0_525
	v_lshl_add_u32 v136, s38, 8, v150
	v_lshrrev_b32_e32 v146, 1, v152
	v_lshl_add_u32 v146, s36, 8, v146
	s_movk_i32 s40, 0x800
	s_lshl_b32 s36, s36, 2
	s_ashr_i32 s37, s36, 31
	s_lshl_b64 s[36:37], s[36:37], 2
	s_add_u32 s36, s61, s36
	s_addc_u32 s37, s62, s37
	v_and_b32_e32 v190, 63, v202
	v_xor_b32_e32 v191, 32, v190
	v_xor_b32_e32 v190, 16, v190
	v_lshlrev_b32_e32 v190, 2, v190
	v_lshlrev_b32_e32 v191, 2, v191
	v_lshlrev_b32_e32 v200, 7, v136
	v_pk_mul_f32 v[184:185], v[112:113], v[112:113]
	v_pk_fma_f32 v[184:185], v[114:115], v[114:115], v[184:185]
	v_pk_fma_f32 v[184:185], v[116:117], v[116:117], v[184:185]
	v_pk_fma_f32 v[184:185], v[118:119], v[118:119], v[184:185]
	v_pk_fma_f32 v[184:185], v[120:121], v[120:121], v[184:185]
	v_pk_fma_f32 v[184:185], v[122:123], v[122:123], v[184:185]
	v_pk_fma_f32 v[184:185], v[124:125], v[124:125], v[184:185]
	v_pk_fma_f32 v[184:185], v[126:127], v[126:127], v[184:185]
	v_add_f32_e32 v176, v184, v185
	v_pk_mul_f32 v[186:187], v[96:97], v[96:97]
	v_pk_fma_f32 v[186:187], v[98:99], v[98:99], v[186:187]
	v_pk_fma_f32 v[186:187], v[100:101], v[100:101], v[186:187]
	v_pk_fma_f32 v[186:187], v[102:103], v[102:103], v[186:187]
	v_pk_fma_f32 v[186:187], v[104:105], v[104:105], v[186:187]
	v_pk_fma_f32 v[186:187], v[106:107], v[106:107], v[186:187]
	v_pk_fma_f32 v[186:187], v[108:109], v[108:109], v[186:187]
	v_pk_fma_f32 v[186:187], v[110:111], v[110:111], v[186:187]
	v_add_f32_e32 v177, v186, v187
	v_pk_mul_f32 v[184:185], v[80:81], v[80:81]
	v_pk_fma_f32 v[184:185], v[82:83], v[82:83], v[184:185]
	v_pk_fma_f32 v[184:185], v[84:85], v[84:85], v[184:185]
	v_pk_fma_f32 v[184:185], v[86:87], v[86:87], v[184:185]
	v_pk_fma_f32 v[184:185], v[88:89], v[88:89], v[184:185]
	v_pk_fma_f32 v[184:185], v[90:91], v[90:91], v[184:185]
	v_pk_fma_f32 v[184:185], v[92:93], v[92:93], v[184:185]
	v_pk_fma_f32 v[184:185], v[94:95], v[94:95], v[184:185]
	v_add_f32_e32 v178, v184, v185
	v_pk_mul_f32 v[186:187], v[64:65], v[64:65]
	v_pk_fma_f32 v[186:187], v[66:67], v[66:67], v[186:187]
	v_pk_fma_f32 v[186:187], v[68:69], v[68:69], v[186:187]
	v_pk_fma_f32 v[186:187], v[70:71], v[70:71], v[186:187]
	v_pk_fma_f32 v[186:187], v[72:73], v[72:73], v[186:187]
	v_pk_fma_f32 v[186:187], v[74:75], v[74:75], v[186:187]
	v_pk_fma_f32 v[186:187], v[76:77], v[76:77], v[186:187]
	v_pk_fma_f32 v[186:187], v[78:79], v[78:79], v[186:187]
	v_add_f32_e32 v179, v186, v187
	v_pk_mul_f32 v[184:185], v[48:49], v[48:49]
	v_pk_fma_f32 v[184:185], v[50:51], v[50:51], v[184:185]
	v_pk_fma_f32 v[184:185], v[52:53], v[52:53], v[184:185]
	v_pk_fma_f32 v[184:185], v[54:55], v[54:55], v[184:185]
	v_pk_fma_f32 v[184:185], v[56:57], v[56:57], v[184:185]
	v_pk_fma_f32 v[184:185], v[58:59], v[58:59], v[184:185]
	v_pk_fma_f32 v[184:185], v[60:61], v[60:61], v[184:185]
	v_pk_fma_f32 v[184:185], v[62:63], v[62:63], v[184:185]
	v_add_f32_e32 v180, v184, v185
	v_pk_mul_f32 v[186:187], v[32:33], v[32:33]
; DI unsigned cvtpk(float lo, float hi) { unsigned r; asm volatile("v_cvt_pk_bf16_f32 %0, %1, %2" : "=v"(r) : "v"(lo), "v"(hi)); return r; }
;     DI void operator()(const f32x4 (&acc)[2][2][4][2], const pg8::Unit& u, int wr, int wc, int fr, int fq) const {
;     ...
;                     s += v0[0] * v0[0] + v0[1] * v0[1] + v0[2] * v0[2] + v0[3] * v0[3] + v1[0] * v1[0] + v1[1] * v1[1] + v1[2] * v1[2] + v1[3] * v1[3];
;                     u32x4 w = {cvtpk(v0[0], v0[1]), cvtpk(v0[2], v0[3]), cvtpk(v1[0], v1[1]), cvtpk(v1[2], v1[3])};
;                     stg128(o2, row * 4096u + c0_ + bj * 256u, w);
;                 }
;                 s += __shfl_xor(s, 16); s += __shfl_xor(s, 32);
	v_pk_fma_f32 v[186:187], v[34:35], v[34:35], v[186:187]
	v_pk_fma_f32 v[186:187], v[36:37], v[36:37], v[186:187]
	v_pk_fma_f32 v[186:187], v[38:39], v[38:39], v[186:187]
	v_pk_fma_f32 v[186:187], v[40:41], v[40:41], v[186:187]
	v_pk_fma_f32 v[186:187], v[42:43], v[42:43], v[186:187]
	v_pk_fma_f32 v[186:187], v[44:45], v[44:45], v[186:187]
	v_pk_fma_f32 v[186:187], v[46:47], v[46:47], v[186:187]
	v_add_f32_e32 v181, v186, v187
	v_pk_mul_f32 v[184:185], v[16:17], v[16:17]
	v_pk_fma_f32 v[184:185], v[18:19], v[18:19], v[184:185]
	v_pk_fma_f32 v[184:185], v[20:21], v[20:21], v[184:185]
	v_pk_fma_f32 v[184:185], v[22:23], v[22:23], v[184:185]
	v_pk_fma_f32 v[184:185], v[24:25], v[24:25], v[184:185]
	v_pk_fma_f32 v[184:185], v[26:27], v[26:27], v[184:185]
	v_pk_fma_f32 v[184:185], v[28:29], v[28:29], v[184:185]
	v_pk_fma_f32 v[184:185], v[30:31], v[30:31], v[184:185]
	v_add_f32_e32 v182, v184, v185
	v_pk_mul_f32 v[186:187], v[0:1], v[0:1]
	v_pk_fma_f32 v[186:187], v[2:3], v[2:3], v[186:187]
	v_pk_fma_f32 v[186:187], v[4:5], v[4:5], v[186:187]
	v_pk_fma_f32 v[186:187], v[6:7], v[6:7], v[186:187]
	v_pk_fma_f32 v[186:187], v[8:9], v[8:9], v[186:187]
	v_pk_fma_f32 v[186:187], v[10:11], v[10:11], v[186:187]
	v_pk_fma_f32 v[186:187], v[12:13], v[12:13], v[186:187]
	v_pk_fma_f32 v[186:187], v[14:15], v[14:15], v[186:187]
	v_add_f32_e32 v183, v186, v187
	ds_bpermute_b32 v192, v190, v176
	ds_bpermute_b32 v193, v190, v177
	ds_bpermute_b32 v194, v190, v178
	ds_bpermute_b32 v195, v190, v179
	ds_bpermute_b32 v196, v190, v180
	ds_bpermute_b32 v197, v190, v181
	ds_bpermute_b32 v198, v190, v182
	ds_bpermute_b32 v199, v190, v183
	s_waitcnt lgkmcnt(7)
	v_add_f32_e32 v176, v176, v192
	s_waitcnt lgkmcnt(6)
	v_add_f32_e32 v177, v177, v193
	s_waitcnt lgkmcnt(5)
	v_add_f32_e32 v178, v178, v194
	s_waitcnt lgkmcnt(4)
	v_add_f32_e32 v179, v179, v195
	s_waitcnt lgkmcnt(3)
	v_add_f32_e32 v180, v180, v196
	s_waitcnt lgkmcnt(2)
	v_add_f32_e32 v181, v181, v197
	s_waitcnt lgkmcnt(1)
	v_add_f32_e32 v182, v182, v198
	s_waitcnt lgkmcnt(0)
	v_add_f32_e32 v183, v183, v199
	ds_bpermute_b32 v192, v191, v176
	ds_bpermute_b32 v193, v191, v177
	ds_bpermute_b32 v194, v191, v178
	ds_bpermute_b32 v195, v191, v179
	ds_bpermute_b32 v196, v191, v180
	ds_bpermute_b32 v197, v191, v181
	ds_bpermute_b32 v198, v191, v182
	ds_bpermute_b32 v199, v191, v183
	s_waitcnt lgkmcnt(7)
	v_add_f32_e32 v176, v176, v192
	s_waitcnt lgkmcnt(6)
	v_add_f32_e32 v177, v177, v193
	s_waitcnt lgkmcnt(5)
	v_add_f32_e32 v178, v178, v194
	s_waitcnt lgkmcnt(4)
	v_add_f32_e32 v179, v179, v195
	s_waitcnt lgkmcnt(3)
	v_add_f32_e32 v180, v180, v196
	s_waitcnt lgkmcnt(2)
	v_add_f32_e32 v181, v181, v197
	s_waitcnt lgkmcnt(1)
	v_add_f32_e32 v182, v182, v198
	s_waitcnt lgkmcnt(0)
	v_add_f32_e32 v183, v183, v199
	v_and_b32_e32 v213, 15, v202
	v_bfe_u32 v214, v202, 2, 4
	v_bfe_u32 v215, v202, 4, 2
	v_and_b32_e32 v216, 3, v202
	v_sub_u32_e32 v217, v214, v213
	v_add_u32_e32 v217, v136, v217
	v_sub_u32_e32 v218, v216, v215
	v_lshl_add_u32 v234, v218, 3, v146
	v_mov_b32_e32 v235, 0
	v_lshl_or_b32 v220, v216, 4, v214
	v_lshlrev_b32_e32 v220, 2, v220
	v_lshl_add_u64 v[236:237], v[234:235], 1, s[18:19]
	v_mov_b32_e32 v239, 0
	v_mul_lo_u32 v238, v217, s40
	v_lshl_add_u64 v[224:225], v[238:239], 1, v[236:237]
	v_cvt_pk_bf16_f32 v160, v124, v125
	v_cvt_pk_bf16_f32 v161, v126, v127
	v_cvt_pk_bf16_f32 v162, v120, v121
	v_cvt_pk_bf16_f32 v163, v122, v123
	ds_bpermute_b32 v124, v220, v160
	ds_bpermute_b32 v125, v220, v161
	ds_bpermute_b32 v126, v220, v162
	ds_bpermute_b32 v127, v220, v163
	v_cvt_pk_bf16_f32 v164, v116, v117
	v_cvt_pk_bf16_f32 v165, v118, v119
	v_cvt_pk_bf16_f32 v166, v112, v113
	v_cvt_pk_bf16_f32 v167, v114, v115
	ds_bpermute_b32 v116, v220, v164
	ds_bpermute_b32 v117, v220, v165
	ds_bpermute_b32 v118, v220, v166
	ds_bpermute_b32 v119, v220, v167
	s_waitcnt lgkmcnt(4)
	global_store_dwordx4 v[224:225], v[124:127], off
	v_add_u32_e32 v238, 16, v217
	v_mul_lo_u32 v238, v238, s40
	v_lshl_add_u64 v[226:227], v[238:239], 1, v[236:237]
	v_cvt_pk_bf16_f32 v168, v108, v109
	v_cvt_pk_bf16_f32 v169, v110, v111
	v_cvt_pk_bf16_f32 v170, v104, v105
	v_cvt_pk_bf16_f32 v171, v106, v107
	ds_bpermute_b32 v108, v220, v168
	ds_bpermute_b32 v109, v220, v169
	ds_bpermute_b32 v110, v220, v170
	ds_bpermute_b32 v111, v220, v171
	s_waitcnt lgkmcnt(4)
	global_store_dwordx4 v[224:225], v[116:119], off offset:256
	v_cvt_pk_bf16_f32 v172, v100, v101
	v_cvt_pk_bf16_f32 v173, v102, v103
	v_cvt_pk_bf16_f32 v174, v96, v97
	v_cvt_pk_bf16_f32 v175, v98, v99
	ds_bpermute_b32 v100, v220, v172
	ds_bpermute_b32 v101, v220, v173
	ds_bpermute_b32 v102, v220, v174
	ds_bpermute_b32 v103, v220, v175
	s_waitcnt lgkmcnt(4)
	global_store_dwordx4 v[226:227], v[108:111], off
	v_add_u32_e32 v238, 32, v217
	v_mul_lo_u32 v238, v238, s40
	v_lshl_add_u64 v[228:229], v[238:239], 1, v[236:237]
	v_cvt_pk_bf16_f32 v160, v92, v93
	v_cvt_pk_bf16_f32 v161, v94, v95
	v_cvt_pk_bf16_f32 v162, v88, v89
	v_cvt_pk_bf16_f32 v163, v90, v91
	ds_bpermute_b32 v92, v220, v160
	ds_bpermute_b32 v93, v220, v161
	ds_bpermute_b32 v94, v220, v162
	ds_bpermute_b32 v95, v220, v163
	s_waitcnt lgkmcnt(4)
; DI unsigned cvtpk(float lo, float hi) { unsigned r; asm volatile("v_cvt_pk_bf16_f32 %0, %1, %2" : "=v"(r) : "v"(lo), "v"(hi)); return r; }
;     DI void operator()(const f32x4 (&acc)[2][2][4][2], const pg8::Unit& u, int wr, int wc, int fr, int fq) const {
;     ...
;                     u32x4 w = {cvtpk(v0[0], v0[1]), cvtpk(v0[2], v0[3]), cvtpk(v1[0], v1[1]), cvtpk(v1[2], v1[3])};
;                     stg128(o2, row * 4096u + c0_ + bj * 256u, w);
;                 }
;                 s += __shfl_xor(s, 16); s += __shfl_xor(s, 32);
;                 if (fq == 0) ssq[(size_t)row * 32 + u.pn * 4 + wc] = s;
	global_store_dwordx4 v[226:227], v[100:103], off offset:256
	v_cvt_pk_bf16_f32 v164, v84, v85
	v_cvt_pk_bf16_f32 v165, v86, v87
	v_cvt_pk_bf16_f32 v166, v80, v81
	v_cvt_pk_bf16_f32 v167, v82, v83
	ds_bpermute_b32 v84, v220, v164
	ds_bpermute_b32 v85, v220, v165
	ds_bpermute_b32 v86, v220, v166
	ds_bpermute_b32 v87, v220, v167
	s_waitcnt lgkmcnt(4)
	global_store_dwordx4 v[228:229], v[92:95], off
	v_add_u32_e32 v238, 48, v217
	v_mul_lo_u32 v238, v238, s40
	v_lshl_add_u64 v[230:231], v[238:239], 1, v[236:237]
	v_cvt_pk_bf16_f32 v168, v76, v77
	v_cvt_pk_bf16_f32 v169, v78, v79
	v_cvt_pk_bf16_f32 v170, v72, v73
	v_cvt_pk_bf16_f32 v171, v74, v75
	ds_bpermute_b32 v76, v220, v168
	ds_bpermute_b32 v77, v220, v169
	ds_bpermute_b32 v78, v220, v170
	ds_bpermute_b32 v79, v220, v171
	s_waitcnt lgkmcnt(4)
	global_store_dwordx4 v[228:229], v[84:87], off offset:256
	v_cvt_pk_bf16_f32 v172, v68, v69
	v_cvt_pk_bf16_f32 v173, v70, v71
	v_cvt_pk_bf16_f32 v174, v64, v65
	v_cvt_pk_bf16_f32 v175, v66, v67
	ds_bpermute_b32 v68, v220, v172
	ds_bpermute_b32 v69, v220, v173
	ds_bpermute_b32 v70, v220, v174
	ds_bpermute_b32 v71, v220, v175
	s_waitcnt lgkmcnt(4)
	global_store_dwordx4 v[230:231], v[76:79], off
	v_add_u32_e32 v238, 0x80, v217
	v_mul_lo_u32 v238, v238, s40
	v_lshl_add_u64 v[224:225], v[238:239], 1, v[236:237]
	v_cvt_pk_bf16_f32 v160, v60, v61
	v_cvt_pk_bf16_f32 v161, v62, v63
	v_cvt_pk_bf16_f32 v162, v56, v57
	v_cvt_pk_bf16_f32 v163, v58, v59
	ds_bpermute_b32 v60, v220, v160
	ds_bpermute_b32 v61, v220, v161
	ds_bpermute_b32 v62, v220, v162
	ds_bpermute_b32 v63, v220, v163
	s_waitcnt lgkmcnt(4)
	global_store_dwordx4 v[230:231], v[68:71], off offset:256
	v_cvt_pk_bf16_f32 v164, v52, v53
	v_cvt_pk_bf16_f32 v165, v54, v55
	v_cvt_pk_bf16_f32 v166, v48, v49
	v_cvt_pk_bf16_f32 v167, v50, v51
	ds_bpermute_b32 v52, v220, v164
	ds_bpermute_b32 v53, v220, v165
	ds_bpermute_b32 v54, v220, v166
	ds_bpermute_b32 v55, v220, v167
	s_waitcnt lgkmcnt(4)
	global_store_dwordx4 v[224:225], v[60:63], off
	v_add_u32_e32 v238, 0x90, v217
	v_mul_lo_u32 v238, v238, s40
	v_lshl_add_u64 v[226:227], v[238:239], 1, v[236:237]
	v_cvt_pk_bf16_f32 v168, v44, v45
	v_cvt_pk_bf16_f32 v169, v46, v47
	v_cvt_pk_bf16_f32 v170, v40, v41
	v_cvt_pk_bf16_f32 v171, v42, v43
	ds_bpermute_b32 v44, v220, v168
	ds_bpermute_b32 v45, v220, v169
	ds_bpermute_b32 v46, v220, v170
	ds_bpermute_b32 v47, v220, v171
	s_waitcnt lgkmcnt(4)
	global_store_dwordx4 v[224:225], v[52:55], off offset:256
	v_cvt_pk_bf16_f32 v172, v36, v37
	v_cvt_pk_bf16_f32 v173, v38, v39
	v_cvt_pk_bf16_f32 v174, v32, v33
	v_cvt_pk_bf16_f32 v175, v34, v35
	ds_bpermute_b32 v36, v220, v172
	ds_bpermute_b32 v37, v220, v173
	ds_bpermute_b32 v38, v220, v174
	ds_bpermute_b32 v39, v220, v175
	s_waitcnt lgkmcnt(4)
	global_store_dwordx4 v[226:227], v[44:47], off
	v_add_u32_e32 v238, 0xa0, v217
	v_mul_lo_u32 v238, v238, s40
	v_lshl_add_u64 v[228:229], v[238:239], 1, v[236:237]
	v_cvt_pk_bf16_f32 v160, v28, v29
	v_cvt_pk_bf16_f32 v161, v30, v31
	v_cvt_pk_bf16_f32 v162, v24, v25
	v_cvt_pk_bf16_f32 v163, v26, v27
	ds_bpermute_b32 v28, v220, v160
	ds_bpermute_b32 v29, v220, v161
	ds_bpermute_b32 v30, v220, v162
	ds_bpermute_b32 v31, v220, v163
	s_waitcnt lgkmcnt(4)
	global_store_dwordx4 v[226:227], v[36:39], off offset:256
	v_cvt_pk_bf16_f32 v164, v20, v21
	v_cvt_pk_bf16_f32 v165, v22, v23
	v_cvt_pk_bf16_f32 v166, v16, v17
	v_cvt_pk_bf16_f32 v167, v18, v19
	ds_bpermute_b32 v20, v220, v164
	ds_bpermute_b32 v21, v220, v165
	ds_bpermute_b32 v22, v220, v166
	ds_bpermute_b32 v23, v220, v167
	s_waitcnt lgkmcnt(4)
	global_store_dwordx4 v[228:229], v[28:31], off
	v_add_u32_e32 v238, 0xb0, v217
	v_mul_lo_u32 v238, v238, s40
	v_lshl_add_u64 v[230:231], v[238:239], 1, v[236:237]
	v_cvt_pk_bf16_f32 v168, v12, v13
	v_cvt_pk_bf16_f32 v169, v14, v15
	v_cvt_pk_bf16_f32 v170, v8, v9
	v_cvt_pk_bf16_f32 v171, v10, v11
	ds_bpermute_b32 v12, v220, v168
	ds_bpermute_b32 v13, v220, v169
	ds_bpermute_b32 v14, v220, v170
	ds_bpermute_b32 v15, v220, v171
	s_waitcnt lgkmcnt(4)
	global_store_dwordx4 v[228:229], v[20:23], off offset:256
	v_cvt_pk_bf16_f32 v172, v4, v5
	v_cvt_pk_bf16_f32 v173, v6, v7
	v_cvt_pk_bf16_f32 v174, v0, v1
	v_cvt_pk_bf16_f32 v175, v2, v3
	ds_bpermute_b32 v4, v220, v172
	ds_bpermute_b32 v5, v220, v173
	ds_bpermute_b32 v6, v220, v174
	ds_bpermute_b32 v7, v220, v175
	s_waitcnt lgkmcnt(4)
	global_store_dwordx4 v[230:231], v[12:15], off
	s_waitcnt lgkmcnt(0)
	global_store_dwordx4 v[230:231], v[4:7], off offset:256
	s_and_saveexec_b64 s[38:39], s[6:7]
	global_store_dword v200, v176, s[36:37]
	v_add_u32_e32 v201, 0x800, v200
	global_store_dword v201, v177, s[36:37]
	v_add_u32_e32 v201, 0x1000, v200
	global_store_dword v201, v178, s[36:37]
	v_add_u32_e32 v201, 0x1800, v200
	global_store_dword v201, v179, s[36:37]
	v_add_u32_e32 v201, 0x4000, v200
	global_store_dword v201, v180, s[36:37]
	v_add_u32_e32 v201, 0x4800, v200
	global_store_dword v201, v181, s[36:37]
	v_add_u32_e32 v201, 0x5000, v200
	global_store_dword v201, v182, s[36:37]
	v_add_u32_e32 v201, 0x5800, v200
	global_store_dword v201, v183, s[36:37]
	s_branch .LBB0_517
